# grid barrier: non-leader workgroups poll the cross-XCD release word (TOPGEN) directly instead of the per-XCD relay word (one atomic hop fewer per barrier); on top of LDS-image U/w_up/w_down layouts
# speedup vs baseline: 1.5411x; 1.0115x over previous
.LBB0_107:
	v_readlane_b32 s38, v250, 46
	v_readlane_b32 s39, v250, 47
	v_cvt_f32_u32_e32 v2, v5
	v_sub_u32_e32 v7, 0, v5
	v_rcp_iflag_f32_e32 v2, v2
	s_nop 1
	global_atomic_add v6, v3, v195, s[38:39] sc0
	v_mul_f32_e32 v2, 0x4f7ffffe, v2
	v_cvt_u32_f32_e32 v2, v2
	v_mul_lo_u32 v7, v7, v2
	v_mul_hi_u32 v7, v2, v7
	v_add_u32_e32 v2, v2, v7
	s_waitcnt vmcnt(0)
	v_mul_hi_u32 v2, v6, v2
	v_mul_lo_u32 v7, v2, v5
	v_sub_u32_e32 v7, v6, v7
	v_add_u32_e32 v8, 1, v2
	v_cmp_ge_u32_e32 vcc, v7, v5
	v_add_u32_e32 v6, 1, v6
	s_nop 0
	v_cndmask_b32_e32 v2, v2, v8, vcc
	v_sub_u32_e32 v8, v7, v5
	v_cndmask_b32_e32 v7, v7, v8, vcc
	v_add_u32_e32 v8, 1, v2
	v_cmp_ge_u32_e32 vcc, v7, v5
	s_nop 1
	v_cndmask_b32_e32 v2, v2, v8, vcc
	v_mul_lo_u32 v7, v5, v2
	v_add_u32_e32 v5, v7, v5
	v_cmp_ne_u32_e32 vcc, v6, v5
	s_and_saveexec_b64 s[38:39], vcc
	s_xor_b64 s[40:41], exec, s[38:39]
	s_cbranch_execz .LBB0_121
	v_readlane_b32 s38, v250, 52
	v_readlane_b32 s39, v250, 53
	s_waitcnt lgkmcnt(0)
	s_nop 3
	global_load_dword v4, v3, s[38:39] sc1
	s_waitcnt vmcnt(0)
	v_cmp_eq_u32_e32 vcc, v4, v2
	s_and_saveexec_b64 s[42:43], vcc
	s_cbranch_execz .LBB0_120
	s_mov_b32 s18, 1
	s_mov_b64 s[44:45], 0
	s_branch .LBB0_111

.LBB0_235:
	v_readlane_b32 s4, v253, 23
	v_readlane_b32 s5, v253, 24
	v_cvt_f32_u32_e32 v1, v3
	v_sub_u32_e32 v5, 0, v3
	v_rcp_iflag_f32_e32 v1, v1
	s_nop 1
	global_atomic_add v4, v19, v210, s[4:5] sc0
	v_mul_f32_e32 v1, 0x4f7ffffe, v1
	v_cvt_u32_f32_e32 v1, v1
	v_mul_lo_u32 v5, v5, v1
	v_mul_hi_u32 v5, v1, v5
	v_add_u32_e32 v1, v1, v5
	s_waitcnt vmcnt(0)
	v_mul_hi_u32 v1, v4, v1
	v_mul_lo_u32 v5, v1, v3
	v_sub_u32_e32 v5, v4, v5
	v_add_u32_e32 v6, 1, v1
	v_cmp_ge_u32_e32 vcc, v5, v3
	v_add_u32_e32 v4, 1, v4
	s_nop 0
	v_cndmask_b32_e32 v1, v1, v6, vcc
	v_sub_u32_e32 v6, v5, v3
	v_cndmask_b32_e32 v5, v5, v6, vcc
	v_add_u32_e32 v6, 1, v1
	v_cmp_ge_u32_e32 vcc, v5, v3
	s_nop 1
	v_cndmask_b32_e32 v1, v1, v6, vcc
	v_mul_lo_u32 v5, v3, v1
	v_add_u32_e32 v3, v5, v3
	v_cmp_ne_u32_e32 vcc, v4, v3
	s_and_saveexec_b64 s[4:5], vcc
	s_xor_b64 s[4:5], exec, s[4:5]
	s_cbranch_execz .LBB0_249
	v_readlane_b32 s6, v253, 29
	v_readlane_b32 s7, v253, 30
	s_waitcnt lgkmcnt(0)
	s_nop 3
	global_load_dword v2, v19, s[6:7] sc1
	s_waitcnt vmcnt(0)
	v_cmp_eq_u32_e32 vcc, v2, v1
	s_and_saveexec_b64 s[6:7], vcc
	s_cbranch_execz .LBB0_248
	s_mov_b32 s18, 1
	s_mov_b64 s[8:9], 0
	s_branch .LBB0_239

.LBB0_352:
	v_readlane_b32 s14, v253, 23
	v_readlane_b32 s15, v253, 24
	v_cvt_f32_u32_e32 v1, v3
	v_sub_u32_e32 v5, 0, v3
	v_rcp_iflag_f32_e32 v1, v1
	s_nop 1
	global_atomic_add v4, v19, v210, s[14:15] sc0
	v_mul_f32_e32 v1, 0x4f7ffffe, v1
	v_cvt_u32_f32_e32 v1, v1
	v_mul_lo_u32 v5, v5, v1
	v_mul_hi_u32 v5, v1, v5
	v_add_u32_e32 v1, v1, v5
	s_waitcnt vmcnt(0)
	v_mul_hi_u32 v1, v4, v1
	v_mul_lo_u32 v5, v1, v3
	v_sub_u32_e32 v5, v4, v5
	v_add_u32_e32 v6, 1, v1
	v_cmp_ge_u32_e32 vcc, v5, v3
	v_add_u32_e32 v4, 1, v4
	s_nop 0
	v_cndmask_b32_e32 v1, v1, v6, vcc
	v_sub_u32_e32 v6, v5, v3
	v_cndmask_b32_e32 v5, v5, v6, vcc
	v_add_u32_e32 v6, 1, v1
	v_cmp_ge_u32_e32 vcc, v5, v3
	s_nop 1
	v_cndmask_b32_e32 v1, v1, v6, vcc
	v_mul_lo_u32 v5, v3, v1
	v_add_u32_e32 v3, v5, v3
	v_cmp_ne_u32_e32 vcc, v4, v3
	s_and_saveexec_b64 s[14:15], vcc
	s_xor_b64 s[14:15], exec, s[14:15]
	s_cbranch_execz .LBB0_366
	v_readlane_b32 s16, v253, 29
	v_readlane_b32 s17, v253, 30
	s_waitcnt lgkmcnt(0)
	s_nop 3
	global_load_dword v2, v19, s[16:17] sc1
	s_waitcnt vmcnt(0)
	v_cmp_eq_u32_e32 vcc, v2, v1
	s_and_saveexec_b64 s[16:17], vcc
	s_cbranch_execz .LBB0_365
	s_mov_b32 s38, 1
	s_mov_b64 s[18:19], 0
	s_branch .LBB0_356

.LBB0_1619:
	v_readlane_b32 s4, v253, 23
	v_readlane_b32 s5, v253, 24
	v_cvt_f32_u32_e32 v1, v3
	v_sub_u32_e32 v5, 0, v3
	v_rcp_iflag_f32_e32 v1, v1
	s_nop 1
	global_atomic_add v4, v19, v210, s[4:5] sc0
	v_mul_f32_e32 v1, 0x4f7ffffe, v1
	v_cvt_u32_f32_e32 v1, v1
	v_mul_lo_u32 v5, v5, v1
	v_mul_hi_u32 v5, v1, v5
	v_add_u32_e32 v1, v1, v5
	s_waitcnt vmcnt(0)
	v_mul_hi_u32 v1, v4, v1
	v_mul_lo_u32 v5, v1, v3
	v_sub_u32_e32 v5, v4, v5
	v_add_u32_e32 v6, 1, v1
	v_cmp_ge_u32_e32 vcc, v5, v3
	v_add_u32_e32 v4, 1, v4
	s_nop 0
	v_cndmask_b32_e32 v1, v1, v6, vcc
	v_sub_u32_e32 v6, v5, v3
	v_cndmask_b32_e32 v5, v5, v6, vcc
	v_add_u32_e32 v6, 1, v1
	v_cmp_ge_u32_e32 vcc, v5, v3
	s_nop 1
	v_cndmask_b32_e32 v1, v1, v6, vcc
	v_mul_lo_u32 v5, v3, v1
	v_add_u32_e32 v3, v5, v3
	v_cmp_ne_u32_e32 vcc, v4, v3
	s_and_saveexec_b64 s[4:5], vcc
	s_xor_b64 s[4:5], exec, s[4:5]
	s_cbranch_execz .LBB0_1633
	v_readlane_b32 s6, v253, 29
	v_readlane_b32 s7, v253, 30
	s_waitcnt lgkmcnt(0)
	s_nop 3
	global_load_dword v2, v19, s[6:7] sc1
	s_waitcnt vmcnt(0)
	v_cmp_eq_u32_e32 vcc, v2, v1
	s_and_saveexec_b64 s[6:7], vcc
	s_cbranch_execz .LBB0_1632
	s_mov_b32 s19, 1
	s_mov_b64 s[8:9], 0
	s_branch .LBB0_1623

.LBB0_1806:
	v_readlane_b32 s8, v253, 23
	v_readlane_b32 s9, v253, 24
	v_cvt_f32_u32_e32 v1, v3
	v_sub_u32_e32 v5, 0, v3
	v_rcp_iflag_f32_e32 v1, v1
	s_nop 1
	global_atomic_add v4, v19, v210, s[8:9] sc0
	v_mul_f32_e32 v1, 0x4f7ffffe, v1
	v_cvt_u32_f32_e32 v1, v1
	v_mul_lo_u32 v5, v5, v1
	v_mul_hi_u32 v5, v1, v5
	v_add_u32_e32 v1, v1, v5
	s_waitcnt vmcnt(0)
	v_mul_hi_u32 v1, v4, v1
	v_mul_lo_u32 v5, v1, v3
	v_sub_u32_e32 v5, v4, v5
	v_add_u32_e32 v6, 1, v1
	v_cmp_ge_u32_e32 vcc, v5, v3
	v_add_u32_e32 v4, 1, v4
	s_nop 0
	v_cndmask_b32_e32 v1, v1, v6, vcc
	v_sub_u32_e32 v6, v5, v3
	v_cndmask_b32_e32 v5, v5, v6, vcc
	v_add_u32_e32 v6, 1, v1
	v_cmp_ge_u32_e32 vcc, v5, v3
	s_nop 1
	v_cndmask_b32_e32 v1, v1, v6, vcc
	v_mul_lo_u32 v5, v3, v1
	v_add_u32_e32 v3, v5, v3
	v_cmp_ne_u32_e32 vcc, v4, v3
	s_and_saveexec_b64 s[8:9], vcc
	s_xor_b64 s[8:9], exec, s[8:9]
	s_cbranch_execz .LBB0_1820
	v_readlane_b32 s10, v253, 29
	v_readlane_b32 s11, v253, 30
	s_waitcnt lgkmcnt(0)
	s_nop 3
	global_load_dword v2, v19, s[10:11] sc1
	s_waitcnt vmcnt(0)
	v_cmp_eq_u32_e32 vcc, v2, v1
	s_and_saveexec_b64 s[10:11], vcc
	s_cbranch_execz .LBB0_1819
	s_mov_b32 s22, 1
	s_mov_b64 s[12:13], 0
	s_branch .LBB0_1810
